# fused epilogues: pass-2 column vectors (gb, sb) touched right after the second exchange barrier so the real loads hit the vector cache instead of exposing an L2 round trip before pass 2
# speedup vs baseline: 1.0087x; 1.0001x over previous
.LBB0_648:
	s_waitcnt vmcnt(0) lgkmcnt(0)
	s_barrier
	s_mov_b32 s100, 0x102000
	s_mov_b32 s101, 0
	v_lshl_add_u64 v[216:217], v[148:149], 2, s[34:35]
	v_lshl_add_u64 v[218:219], v[216:217], 0, s[100:101]
	s_mov_b32 s100, 0x104000
	v_lshl_add_u64 v[220:221], v[216:217], 0, s[100:101]
	global_load_dwordx4 v[252:255], v[218:219], off
	global_load_dwordx4 v[252:255], v[218:219], off offset:64
	global_load_dwordx4 v[252:255], v[218:219], off offset:512
	global_load_dwordx4 v[252:255], v[218:219], off offset:576
	global_load_dwordx4 v[252:255], v[220:221], off
	global_load_dwordx4 v[252:255], v[220:221], off offset:64
	global_load_dwordx4 v[252:255], v[220:221], off offset:512
	global_load_dwordx4 v[252:255], v[220:221], off offset:576
	v_mov_b32_e32 v130, 0
	ds_read_b32 v187, v130 offset:10240
	v_lshlrev_b64 v[180:181], 10, v[150:151]
	v_lshlrev_b64 v[178:179], 10, v[152:153]
	v_lshlrev_b64 v[176:177], 10, v[154:155]
	v_lshlrev_b64 v[174:175], 10, v[156:157]
	v_lshlrev_b64 v[172:173], 10, v[158:159]
	v_lshlrev_b64 v[170:171], 10, v[160:161]
	v_lshlrev_b64 v[168:169], 10, v[164:165]
	v_lshlrev_b64 v[164:165], 10, v[166:167]
	s_and_saveexec_b64 s[4:5], s[6:7]
	s_cbranch_execz .LBB0_650
	s_waitcnt lgkmcnt(1)
	v_lshlrev_b64 v[132:133], 5, v[146:147]
	v_lshl_add_u64 v[132:133], s[62:63], 0, v[132:133]
	global_load_dwordx2 v[134:135], v[132:133], off sc1
	global_load_dwordx2 v[136:137], v[132:133], off offset:8 sc1
	global_load_dwordx2 v[138:139], v[132:133], off offset:16 sc1
	s_nop 0
	global_load_dwordx2 v[132:133], v[132:133], off offset:24 sc1
	s_mov_b32 s0, 0xf800000
	s_waitcnt vmcnt(3)
	v_add_f32_e32 v131, 0, v134
	s_waitcnt vmcnt(2)
	v_add_f32_e32 v131, v131, v136
	s_waitcnt vmcnt(1)
	v_add_f32_e32 v131, v131, v138
	s_waitcnt vmcnt(0)
	v_add_f32_e32 v131, v131, v132
	v_fmamk_f32 v134, v131, 0xbe800000, v134
	v_mul_f32_e32 v140, 0x3e800000, v131
	v_fmamk_f32 v136, v131, 0xbe800000, v136
	v_fmamk_f32 v138, v131, 0xbe800000, v138
	v_fmamk_f32 v131, v131, 0xbe800000, v132
	v_mul_f32_e32 v132, 0x43800000, v134
	v_mul_f32_e32 v141, 0x43800000, v136
	v_mul_f32_e32 v143, 0x43800000, v131
	v_fmac_f32_e32 v135, v134, v132
	v_mul_f32_e32 v142, 0x43800000, v138
	v_fmac_f32_e32 v137, v136, v141
	v_fmac_f32_e32 v133, v131, v143
	v_add_f32_e32 v131, 0, v135
	v_fmac_f32_e32 v139, v138, v142
	v_add_f32_e32 v131, v137, v131
	v_add_f32_e32 v131, v139, v131
	v_add_f32_e32 v131, v133, v131
	v_mul_f32_e32 v131, 0x3a800000, v131
	v_fmac_f32_e32 v131, v140, v140
	v_add_f32_e32 v131, 0x358637bd, v131
	v_mul_f32_e32 v132, 0x4f800000, v131
	v_cmp_gt_f32_e32 vcc, s0, v131
	v_mov_b32_e32 v133, 0x260
	s_nop 0
	v_cndmask_b32_e32 v131, v131, v132, vcc
	v_sqrt_f32_e32 v132, v131
	s_nop 0
	v_add_u32_e32 v134, -1, v132
	v_add_u32_e32 v135, 1, v132
	v_fma_f32 v136, -v134, v132, v131
	v_fma_f32 v137, -v135, v132, v131
	v_cmp_ge_f32_e64 s[0:1], 0, v136
	s_nop 1
	v_cndmask_b32_e64 v132, v132, v134, s[0:1]
	v_cmp_lt_f32_e64 s[0:1], 0, v137
	s_nop 1
	v_cndmask_b32_e64 v132, v132, v135, s[0:1]
	v_mul_f32_e32 v134, 0x37800000, v132
	v_cndmask_b32_e32 v132, v132, v134, vcc
	v_cmp_class_f32_e32 vcc, v131, v133
	s_nop 1
	v_cndmask_b32_e32 v131, v132, v131, vcc
	v_div_scale_f32 v132, s[0:1], v131, v131, 1.0
	v_rcp_f32_e32 v133, v132
	v_div_scale_f32 v134, vcc, 1.0, v131, 1.0
	v_fma_f32 v135, -v132, v133, 1.0
	v_fmac_f32_e32 v133, v135, v133
	v_mul_f32_e32 v135, v134, v133
	v_fma_f32 v136, -v132, v135, v134
	v_fmac_f32_e32 v135, v136, v133
	v_fma_f32 v132, -v132, v135, v134
	v_div_fmas_f32 v132, v132, v133, v135
	v_div_fixup_f32 v131, v132, v131, 1.0
	ds_write_b64 v186, v[130:131] offset:8192

.LBB0_934:
	s_waitcnt vmcnt(0) lgkmcnt(0)
	s_barrier
	s_mov_b32 s100, 0x108000
	s_mov_b32 s101, 0
	v_lshl_add_u64 v[218:219], v[148:149], 0, s[100:101]
	s_mov_b32 s100, 0x10a000
	v_lshl_add_u64 v[220:221], v[148:149], 0, s[100:101]
	global_load_dwordx4 v[252:255], v[218:219], off
	global_load_dwordx4 v[252:255], v[218:219], off offset:64
	global_load_dwordx4 v[252:255], v[218:219], off offset:512
	global_load_dwordx4 v[252:255], v[218:219], off offset:576
	global_load_dwordx4 v[252:255], v[220:221], off
	global_load_dwordx4 v[252:255], v[220:221], off offset:64
	global_load_dwordx4 v[252:255], v[220:221], off offset:512
	global_load_dwordx4 v[252:255], v[220:221], off offset:576
	v_mov_b32_e32 v130, 0
	ds_read_b32 v188, v130 offset:10240
	v_lshlrev_b64 v[180:181], 10, v[150:151]
	v_lshlrev_b64 v[178:179], 10, v[152:153]
	v_lshlrev_b64 v[176:177], 10, v[154:155]
	v_lshlrev_b64 v[174:175], 10, v[156:157]
	v_lshlrev_b64 v[172:173], 10, v[158:159]
	v_lshlrev_b64 v[170:171], 10, v[160:161]
	v_lshlrev_b64 v[168:169], 10, v[164:165]
	v_lshlrev_b64 v[164:165], 10, v[166:167]
	s_and_saveexec_b64 s[6:7], s[8:9]
	s_cbranch_execz .LBB0_936
	s_waitcnt lgkmcnt(1)
	v_lshlrev_b64 v[132:133], 5, v[146:147]
	v_lshl_add_u64 v[132:133], s[64:65], 0, v[132:133]
	global_load_dwordx2 v[134:135], v[132:133], off sc1
	global_load_dwordx2 v[136:137], v[132:133], off offset:8 sc1
	global_load_dwordx2 v[138:139], v[132:133], off offset:16 sc1
	s_nop 0
	global_load_dwordx2 v[132:133], v[132:133], off offset:24 sc1
	s_mov_b32 s0, 0xf800000
	s_waitcnt vmcnt(3)
	v_add_f32_e32 v131, 0, v134
	s_waitcnt vmcnt(2)
	v_add_f32_e32 v131, v131, v136
	s_waitcnt vmcnt(1)
	v_add_f32_e32 v131, v131, v138
	s_waitcnt vmcnt(0)
	v_add_f32_e32 v131, v131, v132
	v_fmamk_f32 v134, v131, 0xbe800000, v134
	v_mul_f32_e32 v140, 0x3e800000, v131
	v_fmamk_f32 v136, v131, 0xbe800000, v136
	v_fmamk_f32 v138, v131, 0xbe800000, v138
	v_fmamk_f32 v131, v131, 0xbe800000, v132
	v_mul_f32_e32 v132, 0x43800000, v134
	v_mul_f32_e32 v141, 0x43800000, v136
	v_mul_f32_e32 v143, 0x43800000, v131
	v_fmac_f32_e32 v135, v134, v132
	v_mul_f32_e32 v142, 0x43800000, v138
	v_fmac_f32_e32 v137, v136, v141
	v_fmac_f32_e32 v133, v131, v143
	v_add_f32_e32 v131, 0, v135
	v_fmac_f32_e32 v139, v138, v142
	v_add_f32_e32 v131, v137, v131
	v_add_f32_e32 v131, v139, v131
	v_add_f32_e32 v131, v133, v131
	v_mul_f32_e32 v131, 0x3a800000, v131
	v_fmac_f32_e32 v131, v140, v140
	v_add_f32_e32 v131, 0x358637bd, v131
	v_mul_f32_e32 v132, 0x4f800000, v131
	v_cmp_gt_f32_e32 vcc, s0, v131
	v_mov_b32_e32 v133, 0x260
	s_nop 0
	v_cndmask_b32_e32 v131, v131, v132, vcc
	v_sqrt_f32_e32 v132, v131
	s_nop 0
	v_add_u32_e32 v134, -1, v132
	v_add_u32_e32 v135, 1, v132
	v_fma_f32 v136, -v134, v132, v131
	v_fma_f32 v137, -v135, v132, v131
	v_cmp_ge_f32_e64 s[0:1], 0, v136
	s_nop 1
	v_cndmask_b32_e64 v132, v132, v134, s[0:1]
	v_cmp_lt_f32_e64 s[0:1], 0, v137
	s_nop 1
	v_cndmask_b32_e64 v132, v132, v135, s[0:1]
	v_mul_f32_e32 v134, 0x37800000, v132
	v_cndmask_b32_e32 v132, v132, v134, vcc
	v_cmp_class_f32_e32 vcc, v131, v133
	s_nop 1
	v_cndmask_b32_e32 v131, v132, v131, vcc
	v_div_scale_f32 v132, s[0:1], v131, v131, 1.0
	v_rcp_f32_e32 v133, v132
	v_div_scale_f32 v134, vcc, 1.0, v131, 1.0
	v_fma_f32 v135, -v132, v133, 1.0
	v_fmac_f32_e32 v133, v135, v133
	v_mul_f32_e32 v135, v134, v133
	v_fma_f32 v136, -v132, v135, v134
	v_fmac_f32_e32 v135, v136, v133
	v_fma_f32 v132, -v132, v135, v134
	v_div_fmas_f32 v132, v132, v133, v135
	v_div_fixup_f32 v131, v132, v131, 1.0
	ds_write_b64 v187, v[130:131] offset:8192

.LBB0_1529:
	s_waitcnt vmcnt(0) lgkmcnt(0)
	s_barrier
	s_mov_b32 s100, 0x10e000
	s_mov_b32 s101, 0
	v_lshl_add_u64 v[218:219], v[148:149], 0, s[100:101]
	s_mov_b32 s100, 0x110000
	v_lshl_add_u64 v[220:221], v[148:149], 0, s[100:101]
	global_load_dwordx4 v[252:255], v[218:219], off
	global_load_dwordx4 v[252:255], v[218:219], off offset:64
	global_load_dwordx4 v[252:255], v[218:219], off offset:512
	global_load_dwordx4 v[252:255], v[218:219], off offset:576
	global_load_dwordx4 v[252:255], v[220:221], off
	global_load_dwordx4 v[252:255], v[220:221], off offset:64
	global_load_dwordx4 v[252:255], v[220:221], off offset:512
	global_load_dwordx4 v[252:255], v[220:221], off offset:576
	v_mov_b32_e32 v130, 0
	ds_read_b32 v186, v130 offset:10240
	v_lshlrev_b64 v[180:181], 10, v[150:151]
	v_lshlrev_b64 v[178:179], 10, v[152:153]
	v_lshlrev_b64 v[176:177], 10, v[154:155]
	v_lshlrev_b64 v[174:175], 10, v[156:157]
	v_lshlrev_b64 v[172:173], 10, v[158:159]
	v_lshlrev_b64 v[170:171], 10, v[160:161]
	v_lshlrev_b64 v[168:169], 10, v[164:165]
	v_lshlrev_b64 v[164:165], 10, v[166:167]
	s_and_saveexec_b64 s[6:7], s[8:9]
	s_cbranch_execz .LBB0_1531
	s_waitcnt lgkmcnt(1)
	v_lshlrev_b64 v[132:133], 5, v[146:147]
	v_lshl_add_u64 v[132:133], s[62:63], 0, v[132:133]
	global_load_dwordx2 v[134:135], v[132:133], off sc1
	global_load_dwordx2 v[136:137], v[132:133], off offset:8 sc1
	global_load_dwordx2 v[138:139], v[132:133], off offset:16 sc1
	s_nop 0
	global_load_dwordx2 v[132:133], v[132:133], off offset:24 sc1
	s_mov_b32 s0, 0xf800000
	s_waitcnt vmcnt(3)
	v_add_f32_e32 v131, 0, v134
	s_waitcnt vmcnt(2)
	v_add_f32_e32 v131, v131, v136
	s_waitcnt vmcnt(1)
	v_add_f32_e32 v131, v131, v138
	s_waitcnt vmcnt(0)
	v_add_f32_e32 v131, v131, v132
	v_fmamk_f32 v134, v131, 0xbe800000, v134
	v_mul_f32_e32 v140, 0x3e800000, v131
	v_fmamk_f32 v136, v131, 0xbe800000, v136
	v_fmamk_f32 v138, v131, 0xbe800000, v138
	v_fmamk_f32 v131, v131, 0xbe800000, v132
	v_mul_f32_e32 v132, 0x43800000, v134
	v_mul_f32_e32 v141, 0x43800000, v136
	v_mul_f32_e32 v143, 0x43800000, v131
	v_fmac_f32_e32 v135, v134, v132
	v_mul_f32_e32 v142, 0x43800000, v138
	v_fmac_f32_e32 v137, v136, v141
	v_fmac_f32_e32 v133, v131, v143
	v_add_f32_e32 v131, 0, v135
	v_fmac_f32_e32 v139, v138, v142
	v_add_f32_e32 v131, v137, v131
	v_add_f32_e32 v131, v139, v131
	v_add_f32_e32 v131, v133, v131
	v_mul_f32_e32 v131, 0x3a800000, v131
	v_fmac_f32_e32 v131, v140, v140
	v_add_f32_e32 v131, 0x358637bd, v131
	v_mul_f32_e32 v132, 0x4f800000, v131
	v_cmp_gt_f32_e32 vcc, s0, v131
	v_mov_b32_e32 v133, 0x260
	s_nop 0
	v_cndmask_b32_e32 v131, v131, v132, vcc
	v_sqrt_f32_e32 v132, v131
	s_nop 0
	v_add_u32_e32 v134, -1, v132
	v_add_u32_e32 v135, 1, v132
	v_fma_f32 v136, -v134, v132, v131
	v_fma_f32 v137, -v135, v132, v131
	v_cmp_ge_f32_e64 s[0:1], 0, v136
	s_nop 1
	v_cndmask_b32_e64 v132, v132, v134, s[0:1]
	v_cmp_lt_f32_e64 s[0:1], 0, v137
	s_nop 1
	v_cndmask_b32_e64 v132, v132, v135, s[0:1]
	v_mul_f32_e32 v134, 0x37800000, v132
	v_cndmask_b32_e32 v132, v132, v134, vcc
	v_cmp_class_f32_e32 vcc, v131, v133
	s_nop 1
	v_cndmask_b32_e32 v131, v132, v131, vcc
	v_div_scale_f32 v132, s[0:1], v131, v131, 1.0
	v_rcp_f32_e32 v133, v132
	v_div_scale_f32 v134, vcc, 1.0, v131, 1.0
	v_fma_f32 v135, -v132, v133, 1.0
	v_fmac_f32_e32 v133, v135, v133
	v_mul_f32_e32 v135, v134, v133
	v_fma_f32 v136, -v132, v135, v134
	v_fmac_f32_e32 v135, v136, v133
	v_fma_f32 v132, -v132, v135, v134
	v_div_fmas_f32 v132, v132, v133, v135
	v_div_fixup_f32 v131, v132, v131, 1.0
	ds_write_b64 v185, v[130:131] offset:8192
